# out-proj: MFMA operands swapped + hand-written epilogue (permlane32/16 exchange of the two 16-col blocks, one 16-byte store per lane; was 128 two-byte stores per lane), on top of the same change for t
# speedup vs baseline: 1.0211x; 1.0104x over previous
; DI u16 f2bf(float x) { unsigned u = __float_as_uint(x); u += 0x7fffu + ((u >> 16) & 1u); return (u16)(u >> 16); }
; DI void phase_outproj(const Params& p, int layer, char* lds) {
;     ...
;     u16* yo = (u16*)(p.ws + OFF_XB) + base;
; #pragma unroll
;     for (int ai = 0; ai < 2; ++ai)
; #pragma unroll
;       for (int bj = 0; bj < 2; ++bj)
; #pragma unroll
;         for (int m = 0; m < 4; ++m) {
; #pragma unroll
;           for (int n = 0; n < 2; ++n)
; #pragma unroll
;             for (int j = 0; j < 4; ++j) yo[(ai * 128 + m * 16 + j) * DM + bj * 128 + n * 16] = f2bf(acc[ai][bj][m][n][j]);
;           __builtin_amdgcn_sched_barrier(0);
;         }
.LBB0_521:
	s_or_b64 exec, exec, s[8:9]
	s_nop 7
	v_and_b32_e32 v140, 64, v4
	v_and_b32_e32 v141, 15, v142
	v_add_u32_e32 v140, v140, v141
	v_bfe_u32 v141, v4, 2, 2
	v_and_b32_e32 v144, 0x60, v142
	v_lshl_add_u32 v144, v141, 3, v144
	v_lshlrev_b32_e32 v134, 11, v140
	v_lshl_add_u32 v134, v144, 1, v134
	s_lshl_b32 s10, s6, 11
	s_lshl_b32 s11, s4, 1
	s_add_u32 s10, s10, s11
	s_add_u32 s10, s78, s10
	s_addc_u32 s11, s79, 0
	v_cvt_pk_bf16_f32 v136, v126, v127
	v_cvt_pk_bf16_f32 v137, v128, v129
	v_cvt_pk_bf16_f32 v138, v122, v123
	v_cvt_pk_bf16_f32 v139, v124, v125
	s_nop 0
	v_permlane32_swap_b32_e32 v136, v138
	v_permlane32_swap_b32_e32 v137, v139
	s_nop 0
	v_permlane16_swap_b32_e32 v136, v138
	v_permlane16_swap_b32_e32 v137, v139
	global_store_dwordx4 v134, v[136:139], s[10:11]
	s_nop 1
	v_cvt_pk_bf16_f32 v136, v94, v95
	v_cvt_pk_bf16_f32 v137, v96, v97
	v_cvt_pk_bf16_f32 v138, v90, v91
	v_cvt_pk_bf16_f32 v139, v92, v93
	s_nop 0
	v_permlane32_swap_b32_e32 v136, v138
	v_permlane32_swap_b32_e32 v137, v139
	s_nop 0
	v_permlane16_swap_b32_e32 v136, v138
	v_permlane16_swap_b32_e32 v137, v139
	global_store_dwordx4 v134, v[136:139], s[10:11] offset:256
	s_nop 1
	v_add_u32_e32 v135, 0x8000, v134
	v_cvt_pk_bf16_f32 v136, v118, v119
	v_cvt_pk_bf16_f32 v137, v120, v121
	v_cvt_pk_bf16_f32 v138, v114, v115
	v_cvt_pk_bf16_f32 v139, v116, v117
	s_nop 0
	v_permlane32_swap_b32_e32 v136, v138
	v_permlane32_swap_b32_e32 v137, v139
	s_nop 0
	v_permlane16_swap_b32_e32 v136, v138
	v_permlane16_swap_b32_e32 v137, v139
	global_store_dwordx4 v135, v[136:139], s[10:11]
	s_nop 1
	v_cvt_pk_bf16_f32 v136, v86, v87
	v_cvt_pk_bf16_f32 v137, v88, v89
	v_cvt_pk_bf16_f32 v138, v82, v83
	v_cvt_pk_bf16_f32 v139, v84, v85
	s_nop 0
	v_permlane32_swap_b32_e32 v136, v138
	v_permlane32_swap_b32_e32 v137, v139
	s_nop 0
	v_permlane16_swap_b32_e32 v136, v138
	v_permlane16_swap_b32_e32 v137, v139
	global_store_dwordx4 v135, v[136:139], s[10:11] offset:256
	s_nop 1
	v_add_u32_e32 v135, 0x10000, v134
	v_cvt_pk_bf16_f32 v136, v110, v111
	v_cvt_pk_bf16_f32 v137, v112, v113
	v_cvt_pk_bf16_f32 v138, v106, v107
	v_cvt_pk_bf16_f32 v139, v108, v109
	s_nop 0
	v_permlane32_swap_b32_e32 v136, v138
	v_permlane32_swap_b32_e32 v137, v139
	s_nop 0
	v_permlane16_swap_b32_e32 v136, v138
	v_permlane16_swap_b32_e32 v137, v139
	global_store_dwordx4 v135, v[136:139], s[10:11]
	s_nop 1
	v_cvt_pk_bf16_f32 v136, v78, v79
	v_cvt_pk_bf16_f32 v137, v80, v81
	v_cvt_pk_bf16_f32 v138, v74, v75
	v_cvt_pk_bf16_f32 v139, v76, v77
	s_nop 0
	v_permlane32_swap_b32_e32 v136, v138
	v_permlane32_swap_b32_e32 v137, v139
	s_nop 0
	v_permlane16_swap_b32_e32 v136, v138
	v_permlane16_swap_b32_e32 v137, v139
	global_store_dwordx4 v135, v[136:139], s[10:11] offset:256
	s_nop 1
	v_add_u32_e32 v135, 0x18000, v134
	v_cvt_pk_bf16_f32 v136, v102, v103
	v_cvt_pk_bf16_f32 v137, v104, v105
	v_cvt_pk_bf16_f32 v138, v98, v99
	v_cvt_pk_bf16_f32 v139, v100, v101
	s_nop 0
	v_permlane32_swap_b32_e32 v136, v138
	v_permlane32_swap_b32_e32 v137, v139
	s_nop 0
	v_permlane16_swap_b32_e32 v136, v138
	v_permlane16_swap_b32_e32 v137, v139
	global_store_dwordx4 v135, v[136:139], s[10:11]
	s_nop 1
	v_cvt_pk_bf16_f32 v136, v70, v71
	v_cvt_pk_bf16_f32 v137, v72, v73
	v_cvt_pk_bf16_f32 v138, v66, v67
	v_cvt_pk_bf16_f32 v139, v68, v69
	s_nop 0
	v_permlane32_swap_b32_e32 v136, v138
	v_permlane32_swap_b32_e32 v137, v139
	s_nop 0
	v_permlane16_swap_b32_e32 v136, v138
	v_permlane16_swap_b32_e32 v137, v139
	global_store_dwordx4 v135, v[136:139], s[10:11] offset:256
	s_nop 1
	v_add_u32_e32 v135, 0x40000, v134
	v_cvt_pk_bf16_f32 v136, v62, v63
	v_cvt_pk_bf16_f32 v137, v64, v65
	v_cvt_pk_bf16_f32 v138, v58, v59
	v_cvt_pk_bf16_f32 v139, v60, v61
	s_nop 0
	v_permlane32_swap_b32_e32 v136, v138
	v_permlane32_swap_b32_e32 v137, v139
	s_nop 0
	v_permlane16_swap_b32_e32 v136, v138
	v_permlane16_swap_b32_e32 v137, v139
	global_store_dwordx4 v135, v[136:139], s[10:11]
	s_nop 1
	v_cvt_pk_bf16_f32 v136, v30, v31
	v_cvt_pk_bf16_f32 v137, v32, v33
	v_cvt_pk_bf16_f32 v138, v26, v27
	v_cvt_pk_bf16_f32 v139, v28, v29
	s_nop 0
	v_permlane32_swap_b32_e32 v136, v138
	v_permlane32_swap_b32_e32 v137, v139
	s_nop 0
	v_permlane16_swap_b32_e32 v136, v138
	v_permlane16_swap_b32_e32 v137, v139
	global_store_dwordx4 v135, v[136:139], s[10:11] offset:256
	s_nop 1
	v_add_u32_e32 v135, 0x48000, v134
	v_cvt_pk_bf16_f32 v136, v54, v55
	v_cvt_pk_bf16_f32 v137, v56, v57
	v_cvt_pk_bf16_f32 v138, v50, v51
	v_cvt_pk_bf16_f32 v139, v52, v53
	s_nop 0
	v_permlane32_swap_b32_e32 v136, v138
	v_permlane32_swap_b32_e32 v137, v139
	s_nop 0
	v_permlane16_swap_b32_e32 v136, v138
	v_permlane16_swap_b32_e32 v137, v139
	global_store_dwordx4 v135, v[136:139], s[10:11]
	s_nop 1
	v_cvt_pk_bf16_f32 v136, v22, v23
	v_cvt_pk_bf16_f32 v137, v24, v25
	v_cvt_pk_bf16_f32 v138, v18, v19
	v_cvt_pk_bf16_f32 v139, v20, v21
	s_nop 0
	v_permlane32_swap_b32_e32 v136, v138
	v_permlane32_swap_b32_e32 v137, v139
	s_nop 0
	v_permlane16_swap_b32_e32 v136, v138
	v_permlane16_swap_b32_e32 v137, v139
	global_store_dwordx4 v135, v[136:139], s[10:11] offset:256
	s_nop 1
	v_add_u32_e32 v135, 0x50000, v134
	v_cvt_pk_bf16_f32 v136, v46, v47
	v_cvt_pk_bf16_f32 v137, v48, v49
	v_cvt_pk_bf16_f32 v138, v42, v43
	v_cvt_pk_bf16_f32 v139, v44, v45
	s_nop 0
	v_permlane32_swap_b32_e32 v136, v138
	v_permlane32_swap_b32_e32 v137, v139
	s_nop 0
	v_permlane16_swap_b32_e32 v136, v138
	v_permlane16_swap_b32_e32 v137, v139
	global_store_dwordx4 v135, v[136:139], s[10:11]
	s_nop 1
	v_cvt_pk_bf16_f32 v136, v14, v15
	v_cvt_pk_bf16_f32 v137, v16, v17
	v_cvt_pk_bf16_f32 v138, v10, v11
	v_cvt_pk_bf16_f32 v139, v12, v13
	s_nop 0
	v_permlane32_swap_b32_e32 v136, v138
	v_permlane32_swap_b32_e32 v137, v139
	s_nop 0
	v_permlane16_swap_b32_e32 v136, v138
	v_permlane16_swap_b32_e32 v137, v139
	global_store_dwordx4 v135, v[136:139], s[10:11] offset:256
	s_nop 1
	v_add_u32_e32 v135, 0x58000, v134
	v_cvt_pk_bf16_f32 v136, v38, v39
	v_cvt_pk_bf16_f32 v137, v40, v41
	v_cvt_pk_bf16_f32 v138, v34, v35
	v_cvt_pk_bf16_f32 v139, v36, v37
	s_nop 0
	v_permlane32_swap_b32_e32 v136, v138
	v_permlane32_swap_b32_e32 v137, v139
	s_nop 0
	v_permlane16_swap_b32_e32 v136, v138
	v_permlane16_swap_b32_e32 v137, v139
	global_store_dwordx4 v135, v[136:139], s[10:11]
	s_nop 1
	v_cvt_pk_bf16_f32 v136, v6, v7
	v_cvt_pk_bf16_f32 v137, v8, v9
	v_cvt_pk_bf16_f32 v138, v0, v1
	v_cvt_pk_bf16_f32 v139, v2, v3
	s_nop 0
	v_permlane32_swap_b32_e32 v136, v138
	v_permlane32_swap_b32_e32 v137, v139
	s_nop 0
	v_permlane16_swap_b32_e32 v136, v138
	v_permlane16_swap_b32_e32 v137, v139
	global_store_dwordx4 v135, v[136:139], s[10:11] offset:256
	s_nop 1
	s_add_i32 s23, s23, s63
	v_readlane_b32 s4, v254, 54
	s_cmp_lt_i32 s23, s4
	s_cbranch_scc0 .LBB0_528

; #define G8_LDA(dst, b, h) for (int m = 0; m < 4; ++m) for (int k = 0; k < 2; ++k) \
;     dst[m][k] = *reinterpret_cast<const bf16x8*>((char*)G8_SA(b, h) + g8_lds_byte(wr * 64 + m * 16 + fr, k * 32 + fq * 8))
; #define G8_LDB(dst, b, h) for (int n = 0; n < 2; ++n) for (int k = 0; k < 2; ++k) \
;     dst[n][k] = *reinterpret_cast<const bf16x8*>((char*)G8_SB(b, h) + g8_lds_byte(wc * 32 + n * 16 + fr, k * 32 + fq * 8))
; #define G8_MMA(ai, bj, At_, Bt_) do { __builtin_amdgcn_s_setprio(1); \
;     for (int m = 0; m < 4; ++m) for (int n = 0; n < 2; ++n) for (int k = 0; k < 2; ++k) \
;       acc[ai][bj][m][n] = __builtin_amdgcn_mfma_f32_16x16x32_bf16(At_[m][k], Bt_[n][k], acc[ai][bj][m][n], 0, 0, 0); \
;     __builtin_amdgcn_s_setprio(0); } while (0)
; #define G8_WV(n) asm volatile("s_waitcnt vmcnt(" #n ")" ::: "memory")
; #define G8_WL(n) asm volatile("s_waitcnt lgkmcnt(" #n ")" ::: "memory")
; #define G8_BAR __builtin_amdgcn_s_barrier()
; #define G8_SCHED __builtin_amdgcn_sched_barrier(0)
; DI void gemm8p(const u16* __restrict__ A, const u16* __restrict__ Bt, int brow, int bcol, f32x4 (&acc)[2][2][4][2]) {
;     ...
;   for (int t = 0; t < nt - 2; t += 2) {
;     G8_LDB(B0, 0, 0); G8_SCHED; G8_LDA(At, 0, 0); G8_STAGE(G8_SA(1, 1), A, brow + HALF, t + 1);
;     G8_WL(8); G8_BAR; G8_WL(0); G8_MMA(0, 0, At, B0); G8_BAR; G8_SCHED;
;     G8_LDB(B1, 0, 1); G8_STAGE(G8_SB(0, 0), Bt, bcol, t + 2);
;     G8_BAR; G8_WL(0); G8_MMA(0, 1, At, B1); G8_BAR;
;     G8_LDA(At, 0, 1); G8_STAGE(G8_SA(0, 0), A, brow, t + 2);
;     G8_BAR; G8_WL(0); G8_MMA(1, 0, At, B0); G8_BAR; G8_SCHED;
;     G8_STAGE(G8_SB(0, 1), Bt, bcol + HALF, t + 2);
;     G8_WV(6); G8_BAR; G8_MMA(1, 1, At, B1); G8_BAR;
.LBB0_525:
	ds_read_b128 v[168:171], v165
	ds_read_b128 v[172:175], v165 offset:1024
	ds_read_b128 v[176:179], v165 offset:2048
	ds_read_b128 v[180:183], v165 offset:3072
	v_add_u32_e32 v166, 0xc000, v150
	v_lshl_add_u64 v[242:243], s[34:35], 0, v[138:139]
	v_readfirstlane_b32 s7, v166
	v_add_u32_e32 v167, 0xe000, v150
	v_lshl_add_u64 v[226:227], v[242:243], 0, s[16:17]
	s_mov_b32 m0, s7
	v_lshl_add_u64 v[244:245], s[34:35], 0, v[140:141]
	v_readfirstlane_b32 s7, v167
	ds_read_b128 v[186:189], v148
	ds_read_b128 v[190:193], v148 offset:1024
	ds_read_b128 v[194:197], v147
	ds_read_b128 v[198:201], v147 offset:1024
	ds_read_b128 v[202:205], v146
	ds_read_b128 v[206:209], v146 offset:1024
	ds_read_b128 v[210:213], v144
	ds_read_b128 v[222:225], v144 offset:1024
	global_load_lds_dwordx4 v[226:227], off
	v_lshl_add_u64 v[226:227], v[244:245], 0, s[16:17]
	s_mov_b32 m0, s7
	s_nop 0
	global_load_lds_dwordx4 v[226:227], off
	s_waitcnt lgkmcnt(8)
	s_barrier
	s_waitcnt lgkmcnt(0)
	s_setprio 1
	s_waitcnt lgkmcnt(0)
	v_mfma_f32_16x16x32_bf16 v[126:129], v[168:171], v[186:189], v[126:129]
	v_mfma_f32_16x16x32_bf16 v[122:125], v[176:179], v[186:189], v[122:125]
	v_mfma_f32_16x16x32_bf16 v[118:121], v[168:171], v[194:197], v[118:121]
	v_mfma_f32_16x16x32_bf16 v[114:117], v[176:179], v[194:197], v[114:117]
	v_mfma_f32_16x16x32_bf16 v[110:113], v[168:171], v[202:205], v[110:113]
	v_mfma_f32_16x16x32_bf16 v[106:109], v[176:179], v[202:205], v[106:109]
	v_mfma_f32_16x16x32_bf16 v[102:105], v[168:171], v[210:213], v[102:105]
	v_mfma_f32_16x16x32_bf16 v[98:101], v[176:179], v[210:213], v[98:101]
	v_mfma_f32_16x16x32_bf16 v[126:129], v[172:175], v[190:193], v[126:129]
	v_mfma_f32_16x16x32_bf16 v[122:125], v[180:183], v[190:193], v[122:125]
	v_mfma_f32_16x16x32_bf16 v[118:121], v[172:175], v[198:201], v[118:121]
	v_mfma_f32_16x16x32_bf16 v[114:117], v[180:183], v[198:201], v[114:117]
	v_mfma_f32_16x16x32_bf16 v[110:113], v[172:175], v[206:209], v[110:113]
	v_mfma_f32_16x16x32_bf16 v[106:109], v[180:183], v[206:209], v[106:109]
	v_mfma_f32_16x16x32_bf16 v[102:105], v[172:175], v[222:225], v[102:105]
	v_mfma_f32_16x16x32_bf16 v[98:101], v[180:183], v[222:225], v[98:101]
	s_setprio 0
	s_barrier
	v_lshl_add_u64 v[246:247], s[34:35], 0, v[134:135]
	v_readfirstlane_b32 s7, v145
	v_lshl_add_u64 v[248:249], v[246:247], 0, s[30:31]
	s_mov_b32 m0, s7
	ds_read_b128 v[226:229], v164
	ds_read_b128 v[230:233], v164 offset:1024
	ds_read_b128 v[234:237], v164 offset:2048
	ds_read_b128 v[238:241], v164 offset:3072
	global_load_lds_dwordx4 v[248:249], off
	v_lshl_add_u64 v[248:249], s[34:35], 0, v[136:137]
	v_readfirstlane_b32 s7, v149
	v_lshl_add_u64 v[250:251], v[248:249], 0, s[30:31]
	s_mov_b32 m0, s7
	s_nop 0
	global_load_lds_dwordx4 v[250:251], off
	s_barrier
	s_waitcnt lgkmcnt(0)
	s_setprio 1
	s_waitcnt lgkmcnt(0)
	v_mfma_f32_16x16x32_bf16 v[94:97], v[226:229], v[186:189], v[94:97]
	v_mfma_f32_16x16x32_bf16 v[90:93], v[234:237], v[186:189], v[90:93]
	v_mfma_f32_16x16x32_bf16 v[86:89], v[226:229], v[194:197], v[86:89]
	v_mfma_f32_16x16x32_bf16 v[82:85], v[234:237], v[194:197], v[82:85]
	v_mfma_f32_16x16x32_bf16 v[78:81], v[226:229], v[202:205], v[78:81]
	v_mfma_f32_16x16x32_bf16 v[74:77], v[234:237], v[202:205], v[74:77]
	v_mfma_f32_16x16x32_bf16 v[70:73], v[226:229], v[210:213], v[70:73]
	v_mfma_f32_16x16x32_bf16 v[66:69], v[234:237], v[210:213], v[66:69]
	v_mfma_f32_16x16x32_bf16 v[94:97], v[230:233], v[190:193], v[94:97]
	v_mfma_f32_16x16x32_bf16 v[90:93], v[238:241], v[190:193], v[90:93]
	v_mfma_f32_16x16x32_bf16 v[86:89], v[230:233], v[198:201], v[86:89]
	v_mfma_f32_16x16x32_bf16 v[82:85], v[238:241], v[198:201], v[82:85]
	v_mfma_f32_16x16x32_bf16 v[78:81], v[230:233], v[206:209], v[78:81]
	v_mfma_f32_16x16x32_bf16 v[74:77], v[238:241], v[206:209], v[74:77]
	v_mfma_f32_16x16x32_bf16 v[70:73], v[230:233], v[222:225], v[70:73]
	v_mfma_f32_16x16x32_bf16 v[66:69], v[238:241], v[222:225], v[66:69]
	s_setprio 0
	v_readfirstlane_b32 s7, v150
	v_lshl_add_u64 v[250:251], v[242:243], 0, s[0:1]
	s_mov_b32 m0, s7
	v_readfirstlane_b32 s7, v151
	s_barrier
	ds_read_b128 v[186:189], v148 offset:16384
	ds_read_b128 v[190:193], v148 offset:17408
	ds_read_b128 v[194:197], v147 offset:16384
	ds_read_b128 v[198:201], v147 offset:17408
	ds_read_b128 v[202:205], v146 offset:16384
	ds_read_b128 v[206:209], v146 offset:17408
	ds_read_b128 v[210:213], v144 offset:16384
	ds_read_b128 v[222:225], v144 offset:17408
	global_load_lds_dwordx4 v[250:251], off
	v_lshl_add_u64 v[250:251], v[244:245], 0, s[0:1]
	s_mov_b32 m0, s7
	s_nop 0
	global_load_lds_dwordx4 v[250:251], off
	s_barrier
	s_waitcnt lgkmcnt(0)
	s_setprio 1
	s_waitcnt lgkmcnt(0)
	v_mfma_f32_16x16x32_bf16 v[62:65], v[168:171], v[186:189], v[62:65]
	v_mfma_f32_16x16x32_bf16 v[58:61], v[176:179], v[186:189], v[58:61]
	v_mfma_f32_16x16x32_bf16 v[54:57], v[168:171], v[194:197], v[54:57]
	v_mfma_f32_16x16x32_bf16 v[50:53], v[176:179], v[194:197], v[50:53]
	v_mfma_f32_16x16x32_bf16 v[46:49], v[168:171], v[202:205], v[46:49]
	v_mfma_f32_16x16x32_bf16 v[42:45], v[176:179], v[202:205], v[42:45]
	v_mfma_f32_16x16x32_bf16 v[38:41], v[168:171], v[210:213], v[38:41]
	v_mfma_f32_16x16x32_bf16 v[34:37], v[176:179], v[210:213], v[34:37]
	v_mfma_f32_16x16x32_bf16 v[62:65], v[172:175], v[190:193], v[62:65]
	v_mfma_f32_16x16x32_bf16 v[58:61], v[180:183], v[190:193], v[58:61]
	v_mfma_f32_16x16x32_bf16 v[54:57], v[172:175], v[198:201], v[54:57]
	v_mfma_f32_16x16x32_bf16 v[50:53], v[180:183], v[198:201], v[50:53]
	v_mfma_f32_16x16x32_bf16 v[46:49], v[172:175], v[206:209], v[46:49]
	v_mfma_f32_16x16x32_bf16 v[42:45], v[180:183], v[206:209], v[42:45]
	v_mfma_f32_16x16x32_bf16 v[38:41], v[172:175], v[222:225], v[38:41]
	v_mfma_f32_16x16x32_bf16 v[34:37], v[180:183], v[222:225], v[34:37]
	s_setprio 0
	s_barrier
; #define G8_LDA(dst, b, h) for (int m = 0; m < 4; ++m) for (int k = 0; k < 2; ++k) \
;     dst[m][k] = *reinterpret_cast<const bf16x8*>((char*)G8_SA(b, h) + g8_lds_byte(wr * 64 + m * 16 + fr, k * 32 + fq * 8))
; #define G8_LDB(dst, b, h) for (int n = 0; n < 2; ++n) for (int k = 0; k < 2; ++k) \
;     dst[n][k] = *reinterpret_cast<const bf16x8*>((char*)G8_SB(b, h) + g8_lds_byte(wc * 32 + n * 16 + fr, k * 32 + fq * 8))
; #define G8_MMA(ai, bj, At_, Bt_) do { __builtin_amdgcn_s_setprio(1); \
;     for (int m = 0; m < 4; ++m) for (int n = 0; n < 2; ++n) for (int k = 0; k < 2; ++k) \
;       acc[ai][bj][m][n] = __builtin_amdgcn_mfma_f32_16x16x32_bf16(At_[m][k], Bt_[n][k], acc[ai][bj][m][n], 0, 0, 0); \
;     __builtin_amdgcn_s_setprio(0); } while (0)
; #define G8_WV(n) asm volatile("s_waitcnt vmcnt(" #n ")" ::: "memory")
; #define G8_WL(n) asm volatile("s_waitcnt lgkmcnt(" #n ")" ::: "memory")
; #define G8_BAR __builtin_amdgcn_s_barrier()
; #define G8_SCHED __builtin_amdgcn_sched_barrier(0)
; DI void gemm8p(const u16* __restrict__ A, const u16* __restrict__ Bt, int brow, int bcol, f32x4 (&acc)[2][2][4][2]) {
;     ...
;     G8_STAGE(G8_SB(0, 1), Bt, bcol + HALF, t + 2);
;     G8_WV(6); G8_BAR; G8_MMA(1, 1, At, B1); G8_BAR;
;     G8_LDB(B0, 1, 0); G8_SCHED; G8_LDA(At, 1, 0); G8_STAGE(G8_SA(0, 1), A, brow + HALF, t + 2);
;     G8_WL(8); G8_BAR; G8_WL(0); G8_MMA(0, 0, At, B0); G8_BAR; G8_SCHED;
;     G8_LDB(B1, 1, 1); G8_STAGE(G8_SB(1, 0), Bt, bcol, t + 3);
;     G8_BAR; G8_WL(0); G8_MMA(0, 1, At, B1); G8_BAR;
;     G8_LDA(At, 1, 1); G8_STAGE(G8_SA(1, 0), A, brow, t + 3);
;     G8_BAR; G8_WL(0); G8_MMA(1, 0, At, B0); G8_BAR; G8_SCHED;
	v_readfirstlane_b32 s7, v153
	v_lshl_add_u64 v[168:169], v[246:247], 0, s[2:3]
	s_mov_b32 m0, s7
	v_readfirstlane_b32 s7, v154
	global_load_lds_dwordx4 v[168:169], off
	v_lshl_add_u64 v[168:169], v[248:249], 0, s[2:3]
	s_mov_b32 m0, s7
	s_nop 0
	global_load_lds_dwordx4 v[168:169], off
	s_waitcnt vmcnt(6)
	s_barrier
	s_setprio 1
	v_mfma_f32_16x16x32_bf16 v[30:33], v[226:229], v[186:189], v[30:33]
	v_mfma_f32_16x16x32_bf16 v[26:29], v[234:237], v[186:189], v[26:29]
	v_mfma_f32_16x16x32_bf16 v[22:25], v[226:229], v[194:197], v[22:25]
	v_mfma_f32_16x16x32_bf16 v[18:21], v[234:237], v[194:197], v[18:21]
	v_mfma_f32_16x16x32_bf16 v[14:17], v[226:229], v[202:205], v[14:17]
	v_mfma_f32_16x16x32_bf16 v[10:13], v[234:237], v[202:205], v[10:13]
	v_mfma_f32_16x16x32_bf16 v[6:9], v[226:229], v[210:213], v[6:9]
	v_mfma_f32_16x16x32_bf16 v[0:3], v[234:237], v[210:213], v[0:3]
	v_mfma_f32_16x16x32_bf16 v[30:33], v[230:233], v[190:193], v[30:33]
	v_mfma_f32_16x16x32_bf16 v[26:29], v[238:241], v[190:193], v[26:29]
	v_mfma_f32_16x16x32_bf16 v[22:25], v[230:233], v[198:201], v[22:25]
	v_mfma_f32_16x16x32_bf16 v[18:21], v[238:241], v[198:201], v[18:21]
	v_mfma_f32_16x16x32_bf16 v[14:17], v[230:233], v[206:209], v[14:17]
	v_mfma_f32_16x16x32_bf16 v[10:13], v[238:241], v[206:209], v[10:13]
	v_mfma_f32_16x16x32_bf16 v[6:9], v[230:233], v[222:225], v[6:9]
	v_mfma_f32_16x16x32_bf16 v[0:3], v[238:241], v[222:225], v[0:3]
	s_setprio 0
	s_barrier
	ds_read_b128 v[168:171], v156
	ds_read_b128 v[172:175], v156 offset:1024
	ds_read_b128 v[176:179], v156 offset:2048
	ds_read_b128 v[180:183], v156 offset:3072
	v_readfirstlane_b32 s7, v155
	v_lshl_add_u64 v[226:227], v[242:243], 0, s[46:47]
	s_mov_b32 m0, s7
	v_readfirstlane_b32 s7, v157
	ds_read_b128 v[186:189], v148 offset:32768
	ds_read_b128 v[190:193], v148 offset:33792
	ds_read_b128 v[194:197], v147 offset:32768
	ds_read_b128 v[198:201], v147 offset:33792
	ds_read_b128 v[202:205], v146 offset:32768
	ds_read_b128 v[206:209], v146 offset:33792
	ds_read_b128 v[210:213], v144 offset:32768
	ds_read_b128 v[222:225], v144 offset:33792
	global_load_lds_dwordx4 v[226:227], off
	v_lshl_add_u64 v[226:227], v[244:245], 0, s[46:47]
	s_mov_b32 m0, s7
	s_nop 0
	global_load_lds_dwordx4 v[226:227], off
	s_waitcnt lgkmcnt(8)
	s_barrier
	s_waitcnt lgkmcnt(0)
	s_setprio 1
	s_waitcnt lgkmcnt(0)
	v_mfma_f32_16x16x32_bf16 v[126:129], v[168:171], v[186:189], v[126:129]
	v_mfma_f32_16x16x32_bf16 v[122:125], v[176:179], v[186:189], v[122:125]
	v_mfma_f32_16x16x32_bf16 v[118:121], v[168:171], v[194:197], v[118:121]
	v_mfma_f32_16x16x32_bf16 v[114:117], v[176:179], v[194:197], v[114:117]
	v_mfma_f32_16x16x32_bf16 v[110:113], v[168:171], v[202:205], v[110:113]
	v_mfma_f32_16x16x32_bf16 v[106:109], v[176:179], v[202:205], v[106:109]
	v_mfma_f32_16x16x32_bf16 v[102:105], v[168:171], v[210:213], v[102:105]
	v_mfma_f32_16x16x32_bf16 v[98:101], v[176:179], v[210:213], v[98:101]
	v_mfma_f32_16x16x32_bf16 v[126:129], v[172:175], v[190:193], v[126:129]
	v_mfma_f32_16x16x32_bf16 v[122:125], v[180:183], v[190:193], v[122:125]
	v_mfma_f32_16x16x32_bf16 v[118:121], v[172:175], v[198:201], v[118:121]
	v_mfma_f32_16x16x32_bf16 v[114:117], v[180:183], v[198:201], v[114:117]
	v_mfma_f32_16x16x32_bf16 v[110:113], v[172:175], v[206:209], v[110:113]
	v_mfma_f32_16x16x32_bf16 v[106:109], v[180:183], v[206:209], v[106:109]
	v_mfma_f32_16x16x32_bf16 v[102:105], v[172:175], v[222:225], v[102:105]
	v_mfma_f32_16x16x32_bf16 v[98:101], v[180:183], v[222:225], v[98:101]
	s_setprio 0
	s_barrier
	v_readfirstlane_b32 s7, v158
	v_lshl_add_u64 v[250:251], v[246:247], 0, s[58:59]
	s_mov_b32 m0, s7
	v_readfirstlane_b32 s7, v159
	ds_read_b128 v[226:229], v152
	ds_read_b128 v[230:233], v152 offset:1024
	ds_read_b128 v[234:237], v152 offset:2048
	ds_read_b128 v[238:241], v152 offset:3072
	global_load_lds_dwordx4 v[250:251], off
	v_lshl_add_u64 v[250:251], v[248:249], 0, s[58:59]
	s_mov_b32 m0, s7
	s_nop 0
	global_load_lds_dwordx4 v[250:251], off
	s_barrier
	s_waitcnt lgkmcnt(0)
	s_setprio 1
	s_waitcnt lgkmcnt(0)
	v_mfma_f32_16x16x32_bf16 v[94:97], v[226:229], v[186:189], v[94:97]
	v_mfma_f32_16x16x32_bf16 v[90:93], v[234:237], v[186:189], v[90:93]
	v_mfma_f32_16x16x32_bf16 v[86:89], v[226:229], v[194:197], v[86:89]
	v_mfma_f32_16x16x32_bf16 v[82:85], v[234:237], v[194:197], v[82:85]
	v_mfma_f32_16x16x32_bf16 v[78:81], v[226:229], v[202:205], v[78:81]
	v_mfma_f32_16x16x32_bf16 v[74:77], v[234:237], v[202:205], v[74:77]
	v_mfma_f32_16x16x32_bf16 v[70:73], v[226:229], v[210:213], v[70:73]
	v_mfma_f32_16x16x32_bf16 v[66:69], v[234:237], v[210:213], v[66:69]
	v_mfma_f32_16x16x32_bf16 v[94:97], v[230:233], v[190:193], v[94:97]
	v_mfma_f32_16x16x32_bf16 v[90:93], v[238:241], v[190:193], v[90:93]
	v_mfma_f32_16x16x32_bf16 v[86:89], v[230:233], v[198:201], v[86:89]
	v_mfma_f32_16x16x32_bf16 v[82:85], v[238:241], v[198:201], v[82:85]
	v_mfma_f32_16x16x32_bf16 v[78:81], v[230:233], v[206:209], v[78:81]
	v_mfma_f32_16x16x32_bf16 v[74:77], v[238:241], v[206:209], v[74:77]
	v_mfma_f32_16x16x32_bf16 v[70:73], v[230:233], v[222:225], v[70:73]
	v_mfma_f32_16x16x32_bf16 v[66:69], v[238:241], v[222:225], v[66:69]
	s_setprio 0
	v_readfirstlane_b32 s7, v160
	v_lshl_add_u64 v[242:243], v[242:243], 0, s[36:37]
	s_mov_b32 m0, s7
	v_readfirstlane_b32 s7, v161
	s_barrier
	ds_read_b128 v[186:189], v148 offset:49152
	ds_read_b128 v[190:193], v148 offset:50176
	ds_read_b128 v[194:197], v147 offset:49152
	ds_read_b128 v[198:201], v147 offset:50176
	ds_read_b128 v[202:205], v146 offset:49152
	ds_read_b128 v[206:209], v146 offset:50176
	ds_read_b128 v[210:213], v144 offset:49152
	ds_read_b128 v[222:225], v144 offset:50176
	global_load_lds_dwordx4 v[242:243], off
	v_lshl_add_u64 v[242:243], v[244:245], 0, s[36:37]
	s_mov_b32 m0, s7
	s_nop 0
	global_load_lds_dwordx4 v[242:243], off
	s_barrier
; #define G8_LDA(dst, b, h) for (int m = 0; m < 4; ++m) for (int k = 0; k < 2; ++k) \
;     dst[m][k] = *reinterpret_cast<const bf16x8*>((char*)G8_SA(b, h) + g8_lds_byte(wr * 64 + m * 16 + fr, k * 32 + fq * 8))
; #define G8_LDB(dst, b, h) for (int n = 0; n < 2; ++n) for (int k = 0; k < 2; ++k) \
;     dst[n][k] = *reinterpret_cast<const bf16x8*>((char*)G8_SB(b, h) + g8_lds_byte(wc * 32 + n * 16 + fr, k * 32 + fq * 8))
; #define G8_MMA(ai, bj, At_, Bt_) do { __builtin_amdgcn_s_setprio(1); \
;     for (int m = 0; m < 4; ++m) for (int n = 0; n < 2; ++n) for (int k = 0; k < 2; ++k) \
;       acc[ai][bj][m][n] = __builtin_amdgcn_mfma_f32_16x16x32_bf16(At_[m][k], Bt_[n][k], acc[ai][bj][m][n], 0, 0, 0); \
;     __builtin_amdgcn_s_setprio(0); } while (0)
; #define G8_WV(n) asm volatile("s_waitcnt vmcnt(" #n ")" ::: "memory")
; #define G8_WL(n) asm volatile("s_waitcnt lgkmcnt(" #n ")" ::: "memory")
; #define G8_BAR __builtin_amdgcn_s_barrier()
; #define G8_SCHED __builtin_amdgcn_sched_barrier(0)
; DI void gemm8p(const u16* __restrict__ A, const u16* __restrict__ Bt, int brow, int bcol, f32x4 (&acc)[2][2][4][2]) {
;     ...
;     G8_BAR; G8_WL(0); G8_MMA(1, 0, At, B0); G8_BAR; G8_SCHED;
;     G8_STAGE(G8_SB(1, 1), Bt, bcol + HALF, t + 3);
;     G8_WV(6); G8_BAR; G8_MMA(1, 1, At, B1); G8_BAR;
;   }
;   { G8_LDB(B0, 0, 0); G8_LDA(At, 0, 0); G8_STAGE(G8_SA(1, 1), A, brow + HALF, nt - 1);
;     G8_BAR; G8_WL(0); G8_MMA(0, 0, At, B0); G8_BAR;
	s_waitcnt lgkmcnt(0)
	s_setprio 1
	s_waitcnt lgkmcnt(0)
	v_mfma_f32_16x16x32_bf16 v[62:65], v[168:171], v[186:189], v[62:65]
	v_mfma_f32_16x16x32_bf16 v[58:61], v[176:179], v[186:189], v[58:61]
	v_mfma_f32_16x16x32_bf16 v[54:57], v[168:171], v[194:197], v[54:57]
	v_mfma_f32_16x16x32_bf16 v[50:53], v[176:179], v[194:197], v[50:53]
	v_mfma_f32_16x16x32_bf16 v[46:49], v[168:171], v[202:205], v[46:49]
	v_mfma_f32_16x16x32_bf16 v[42:45], v[176:179], v[202:205], v[42:45]
	v_mfma_f32_16x16x32_bf16 v[38:41], v[168:171], v[210:213], v[38:41]
	v_mfma_f32_16x16x32_bf16 v[34:37], v[176:179], v[210:213], v[34:37]
	v_mfma_f32_16x16x32_bf16 v[62:65], v[172:175], v[190:193], v[62:65]
	v_mfma_f32_16x16x32_bf16 v[58:61], v[180:183], v[190:193], v[58:61]
	v_mfma_f32_16x16x32_bf16 v[54:57], v[172:175], v[198:201], v[54:57]
	v_mfma_f32_16x16x32_bf16 v[50:53], v[180:183], v[198:201], v[50:53]
	v_mfma_f32_16x16x32_bf16 v[46:49], v[172:175], v[206:209], v[46:49]
	v_mfma_f32_16x16x32_bf16 v[42:45], v[180:183], v[206:209], v[42:45]
	v_mfma_f32_16x16x32_bf16 v[38:41], v[172:175], v[222:225], v[38:41]
	v_mfma_f32_16x16x32_bf16 v[34:37], v[180:183], v[222:225], v[34:37]
	s_setprio 0
	s_barrier
	v_readfirstlane_b32 s7, v162
	v_lshl_add_u64 v[168:169], v[246:247], 0, s[38:39]
	s_mov_b32 m0, s7
	v_readfirstlane_b32 s7, v163
	global_load_lds_dwordx4 v[168:169], off
	v_lshl_add_u64 v[168:169], v[248:249], 0, s[38:39]
	s_mov_b32 m0, s7
	s_nop 0
	global_load_lds_dwordx4 v[168:169], off
	s_waitcnt vmcnt(6)
	s_barrier
	s_setprio 1
	v_mfma_f32_16x16x32_bf16 v[30:33], v[226:229], v[186:189], v[30:33]
	v_mfma_f32_16x16x32_bf16 v[26:29], v[234:237], v[186:189], v[26:29]
	v_mfma_f32_16x16x32_bf16 v[22:25], v[226:229], v[194:197], v[22:25]
	v_mfma_f32_16x16x32_bf16 v[18:21], v[234:237], v[194:197], v[18:21]
	v_mfma_f32_16x16x32_bf16 v[14:17], v[226:229], v[202:205], v[14:17]
	v_mfma_f32_16x16x32_bf16 v[10:13], v[234:237], v[202:205], v[10:13]
	v_mfma_f32_16x16x32_bf16 v[6:9], v[226:229], v[210:213], v[6:9]
	v_mfma_f32_16x16x32_bf16 v[0:3], v[234:237], v[210:213], v[0:3]
	v_mfma_f32_16x16x32_bf16 v[30:33], v[230:233], v[190:193], v[30:33]
	v_mfma_f32_16x16x32_bf16 v[26:29], v[238:241], v[190:193], v[26:29]
	v_mfma_f32_16x16x32_bf16 v[22:25], v[230:233], v[198:201], v[22:25]
	v_mfma_f32_16x16x32_bf16 v[18:21], v[238:241], v[198:201], v[18:21]
	v_mfma_f32_16x16x32_bf16 v[14:17], v[230:233], v[206:209], v[14:17]
	v_mfma_f32_16x16x32_bf16 v[10:13], v[238:241], v[206:209], v[10:13]
	v_mfma_f32_16x16x32_bf16 v[6:9], v[230:233], v[222:225], v[6:9]
	v_mfma_f32_16x16x32_bf16 v[0:3], v[238:241], v[222:225], v[0:3]
	s_setprio 0
	s_add_i32 s5, s5, 2
	v_lshl_add_u64 v[134:135], v[134:135], 0, s[18:19]
	v_lshl_add_u64 v[136:137], v[136:137], 0, s[18:19]
	v_lshl_add_u64 v[138:139], v[138:139], 0, s[18:19]
	s_cmp_lt_u32 s5, 12
	v_lshl_add_u64 v[140:141], v[140:141], 0, s[18:19]
	s_barrier
	s_cbranch_scc1 .LBB0_525
	s_mov_b64 s[8:9], 0x780
	v_readfirstlane_b32 s5, v166
	v_lshl_add_u64 v[130:131], v[130:131], 0, s[8:9]
	s_mov_b32 m0, s5
	v_readfirstlane_b32 s5, v167
	ds_read_b128 v[134:137], v165
	ds_read_b128 v[138:141], v165 offset:1024
	ds_read_b128 v[158:161], v165 offset:2048
	ds_read_b128 v[168:171], v165 offset:3072
	ds_read_b128 v[172:175], v148
	ds_read_b128 v[176:179], v148 offset:1024
	ds_read_b128 v[180:183], v147
	ds_read_b128 v[186:189], v147 offset:1024
	ds_read_b128 v[190:193], v146
	ds_read_b128 v[194:197], v146 offset:1024
	ds_read_b128 v[198:201], v144
	ds_read_b128 v[202:205], v144 offset:1024
	global_load_lds_dwordx4 v[130:131], off
	v_lshl_add_u64 v[130:131], v[132:133], 0, s[8:9]
	s_mov_b32 m0, s5
	s_nop 0
	global_load_lds_dwordx4 v[130:131], off
	s_barrier
	s_waitcnt lgkmcnt(0)
	s_setprio 1
	s_waitcnt lgkmcnt(0)
	v_mfma_f32_16x16x32_bf16 v[126:129], v[134:137], v[172:175], v[126:129]
	v_mfma_f32_16x16x32_bf16 v[122:125], v[158:161], v[172:175], v[122:125]
	v_mfma_f32_16x16x32_bf16 v[118:121], v[134:137], v[180:183], v[118:121]
	v_mfma_f32_16x16x32_bf16 v[114:117], v[158:161], v[180:183], v[114:117]
	v_mfma_f32_16x16x32_bf16 v[110:113], v[134:137], v[190:193], v[110:113]
	v_mfma_f32_16x16x32_bf16 v[106:109], v[158:161], v[190:193], v[106:109]
	v_mfma_f32_16x16x32_bf16 v[102:105], v[134:137], v[198:201], v[102:105]
	v_mfma_f32_16x16x32_bf16 v[98:101], v[158:161], v[198:201], v[98:101]
	v_mfma_f32_16x16x32_bf16 v[126:129], v[138:141], v[176:179], v[126:129]
	v_mfma_f32_16x16x32_bf16 v[122:125], v[168:171], v[176:179], v[122:125]
	v_mfma_f32_16x16x32_bf16 v[118:121], v[138:141], v[186:189], v[118:121]
	v_mfma_f32_16x16x32_bf16 v[114:117], v[168:171], v[186:189], v[114:117]
	v_mfma_f32_16x16x32_bf16 v[110:113], v[138:141], v[194:197], v[110:113]
	v_mfma_f32_16x16x32_bf16 v[106:109], v[168:171], v[194:197], v[106:109]
	v_mfma_f32_16x16x32_bf16 v[102:105], v[138:141], v[202:205], v[102:105]
	v_mfma_f32_16x16x32_bf16 v[98:101], v[168:171], v[202:205], v[98:101]
	s_setprio 0
	s_barrier
	ds_read_b128 v[130:133], v164
	ds_read_b128 v[206:209], v164 offset:1024
	ds_read_b128 v[210:213], v164 offset:2048
	ds_read_b128 v[162:165], v164 offset:3072
	s_barrier
; #define G8_LDA(dst, b, h) for (int m = 0; m < 4; ++m) for (int k = 0; k < 2; ++k) \
;     dst[m][k] = *reinterpret_cast<const bf16x8*>((char*)G8_SA(b, h) + g8_lds_byte(wr * 64 + m * 16 + fr, k * 32 + fq * 8))
; #define G8_LDB(dst, b, h) for (int n = 0; n < 2; ++n) for (int k = 0; k < 2; ++k) \
;     dst[n][k] = *reinterpret_cast<const bf16x8*>((char*)G8_SB(b, h) + g8_lds_byte(wc * 32 + n * 16 + fr, k * 32 + fq * 8))
; #define G8_MMA(ai, bj, At_, Bt_) do { __builtin_amdgcn_s_setprio(1); \
;     for (int m = 0; m < 4; ++m) for (int n = 0; n < 2; ++n) for (int k = 0; k < 2; ++k) \
;       acc[ai][bj][m][n] = __builtin_amdgcn_mfma_f32_16x16x32_bf16(At_[m][k], Bt_[n][k], acc[ai][bj][m][n], 0, 0, 0); \
;     __builtin_amdgcn_s_setprio(0); } while (0)
; #define G8_WV(n) asm volatile("s_waitcnt vmcnt(" #n ")" ::: "memory")
; #define G8_WL(n) asm volatile("s_waitcnt lgkmcnt(" #n ")" ::: "memory")
; #define G8_BAR __builtin_amdgcn_s_barrier()
; DI void gemm8p(const u16* __restrict__ A, const u16* __restrict__ Bt, int brow, int bcol, f32x4 (&acc)[2][2][4][2]) {
;     ...
;     G8_BAR; G8_WL(0); G8_MMA(0, 0, At, B0); G8_BAR;
;     G8_LDB(B1, 0, 1); G8_BAR; G8_WL(0); G8_MMA(0, 1, At, B1); G8_BAR;
;     G8_LDA(At, 0, 1); G8_WV(4); G8_BAR; G8_WL(0); G8_MMA(1, 0, At, B0); G8_MMA(1, 1, At, B1); G8_BAR; }
;   { G8_LDB(B0, 1, 0); G8_LDA(At, 1, 0); G8_WV(2); G8_BAR; G8_WL(0); G8_MMA(0, 0, At, B0); G8_BAR;
	s_waitcnt lgkmcnt(0)
	s_setprio 1
	s_waitcnt lgkmcnt(0)
	v_mfma_f32_16x16x32_bf16 v[94:97], v[130:133], v[172:175], v[94:97]
	v_mfma_f32_16x16x32_bf16 v[90:93], v[210:213], v[172:175], v[90:93]
	v_mfma_f32_16x16x32_bf16 v[86:89], v[130:133], v[180:183], v[86:89]
	v_mfma_f32_16x16x32_bf16 v[82:85], v[210:213], v[180:183], v[82:85]
	v_mfma_f32_16x16x32_bf16 v[78:81], v[130:133], v[190:193], v[78:81]
	v_mfma_f32_16x16x32_bf16 v[74:77], v[210:213], v[190:193], v[74:77]
	v_mfma_f32_16x16x32_bf16 v[70:73], v[130:133], v[198:201], v[70:73]
	v_mfma_f32_16x16x32_bf16 v[66:69], v[210:213], v[198:201], v[66:69]
	v_mfma_f32_16x16x32_bf16 v[94:97], v[206:209], v[176:179], v[94:97]
	v_mfma_f32_16x16x32_bf16 v[90:93], v[162:165], v[176:179], v[90:93]
	v_mfma_f32_16x16x32_bf16 v[86:89], v[206:209], v[186:189], v[86:89]
	v_mfma_f32_16x16x32_bf16 v[82:85], v[162:165], v[186:189], v[82:85]
	v_mfma_f32_16x16x32_bf16 v[78:81], v[206:209], v[194:197], v[78:81]
	v_mfma_f32_16x16x32_bf16 v[74:77], v[162:165], v[194:197], v[74:77]
	v_mfma_f32_16x16x32_bf16 v[70:73], v[206:209], v[202:205], v[70:73]
	v_mfma_f32_16x16x32_bf16 v[66:69], v[162:165], v[202:205], v[66:69]
	s_setprio 0
	s_barrier
	ds_read_b128 v[172:175], v148 offset:16384
	ds_read_b128 v[176:179], v148 offset:17408
	ds_read_b128 v[180:183], v147 offset:16384
	ds_read_b128 v[186:189], v147 offset:17408
	ds_read_b128 v[190:193], v146 offset:16384
	ds_read_b128 v[194:197], v146 offset:17408
	ds_read_b128 v[198:201], v144 offset:16384
	ds_read_b128 v[202:205], v144 offset:17408
	s_waitcnt vmcnt(4)
	s_barrier
	s_waitcnt lgkmcnt(0)
	s_setprio 1
	s_waitcnt lgkmcnt(0)
	v_mfma_f32_16x16x32_bf16 v[62:65], v[134:137], v[172:175], v[62:65]
	v_mfma_f32_16x16x32_bf16 v[58:61], v[158:161], v[172:175], v[58:61]
	v_mfma_f32_16x16x32_bf16 v[54:57], v[134:137], v[180:183], v[54:57]
	v_mfma_f32_16x16x32_bf16 v[50:53], v[158:161], v[180:183], v[50:53]
	v_mfma_f32_16x16x32_bf16 v[46:49], v[134:137], v[190:193], v[46:49]
	v_mfma_f32_16x16x32_bf16 v[42:45], v[158:161], v[190:193], v[42:45]
	v_mfma_f32_16x16x32_bf16 v[38:41], v[134:137], v[198:201], v[38:41]
	v_mfma_f32_16x16x32_bf16 v[34:37], v[158:161], v[198:201], v[34:37]
	v_mfma_f32_16x16x32_bf16 v[62:65], v[138:141], v[176:179], v[62:65]
	v_mfma_f32_16x16x32_bf16 v[58:61], v[168:171], v[176:179], v[58:61]
	v_mfma_f32_16x16x32_bf16 v[54:57], v[138:141], v[186:189], v[54:57]
	v_mfma_f32_16x16x32_bf16 v[50:53], v[168:171], v[186:189], v[50:53]
	v_mfma_f32_16x16x32_bf16 v[46:49], v[138:141], v[194:197], v[46:49]
	v_mfma_f32_16x16x32_bf16 v[42:45], v[168:171], v[194:197], v[42:45]
	v_mfma_f32_16x16x32_bf16 v[38:41], v[138:141], v[202:205], v[38:41]
	v_mfma_f32_16x16x32_bf16 v[34:37], v[168:171], v[202:205], v[34:37]
	s_setprio 0
	s_setprio 1
	v_mfma_f32_16x16x32_bf16 v[30:33], v[130:133], v[172:175], v[30:33]
	v_mfma_f32_16x16x32_bf16 v[26:29], v[210:213], v[172:175], v[26:29]
	v_mfma_f32_16x16x32_bf16 v[22:25], v[130:133], v[180:183], v[22:25]
	v_mfma_f32_16x16x32_bf16 v[18:21], v[210:213], v[180:183], v[18:21]
	v_mfma_f32_16x16x32_bf16 v[14:17], v[130:133], v[190:193], v[14:17]
	v_mfma_f32_16x16x32_bf16 v[10:13], v[210:213], v[190:193], v[10:13]
	v_mfma_f32_16x16x32_bf16 v[6:9], v[130:133], v[198:201], v[6:9]
	v_mfma_f32_16x16x32_bf16 v[0:3], v[210:213], v[198:201], v[0:3]
	v_mfma_f32_16x16x32_bf16 v[30:33], v[206:209], v[176:179], v[30:33]
	v_mfma_f32_16x16x32_bf16 v[26:29], v[162:165], v[176:179], v[26:29]
	v_mfma_f32_16x16x32_bf16 v[22:25], v[206:209], v[186:189], v[22:25]
	v_mfma_f32_16x16x32_bf16 v[18:21], v[162:165], v[186:189], v[18:21]
	v_mfma_f32_16x16x32_bf16 v[14:17], v[206:209], v[194:197], v[14:17]
	v_mfma_f32_16x16x32_bf16 v[10:13], v[162:165], v[194:197], v[10:13]
	v_mfma_f32_16x16x32_bf16 v[6:9], v[206:209], v[202:205], v[6:9]
	v_mfma_f32_16x16x32_bf16 v[0:3], v[162:165], v[202:205], v[0:3]
	s_setprio 0
	s_barrier
	ds_read_b128 v[130:133], v156
	ds_read_b128 v[134:137], v156 offset:1024
	ds_read_b128 v[138:141], v156 offset:2048
	ds_read_b128 v[154:157], v156 offset:3072
	ds_read_b128 v[158:161], v148 offset:32768
	ds_read_b128 v[162:165], v148 offset:33792
	ds_read_b128 v[166:169], v147 offset:32768
	ds_read_b128 v[170:173], v147 offset:33792
	ds_read_b128 v[174:177], v146 offset:32768
	ds_read_b128 v[178:181], v146 offset:33792
	ds_read_b128 v[186:189], v144 offset:32768
	ds_read_b128 v[190:193], v144 offset:33792
	s_waitcnt vmcnt(2)
	s_barrier
; #define G8_LDA(dst, b, h) for (int m = 0; m < 4; ++m) for (int k = 0; k < 2; ++k) \
;     dst[m][k] = *reinterpret_cast<const bf16x8*>((char*)G8_SA(b, h) + g8_lds_byte(wr * 64 + m * 16 + fr, k * 32 + fq * 8))
; #define G8_LDB(dst, b, h) for (int n = 0; n < 2; ++n) for (int k = 0; k < 2; ++k) \
;     dst[n][k] = *reinterpret_cast<const bf16x8*>((char*)G8_SB(b, h) + g8_lds_byte(wc * 32 + n * 16 + fr, k * 32 + fq * 8))
; #define G8_MMA(ai, bj, At_, Bt_) do { __builtin_amdgcn_s_setprio(1); \
;     for (int m = 0; m < 4; ++m) for (int n = 0; n < 2; ++n) for (int k = 0; k < 2; ++k) \
;       acc[ai][bj][m][n] = __builtin_amdgcn_mfma_f32_16x16x32_bf16(At_[m][k], Bt_[n][k], acc[ai][bj][m][n], 0, 0, 0); \
;     __builtin_amdgcn_s_setprio(0); } while (0)
; #define G8_WV(n) asm volatile("s_waitcnt vmcnt(" #n ")" ::: "memory")
; #define G8_WL(n) asm volatile("s_waitcnt lgkmcnt(" #n ")" ::: "memory")
; #define G8_BAR __builtin_amdgcn_s_barrier()
; DI void gemm8p(const u16* __restrict__ A, const u16* __restrict__ Bt, int brow, int bcol, f32x4 (&acc)[2][2][4][2]) {
;     ...
;   { G8_LDB(B0, 1, 0); G8_LDA(At, 1, 0); G8_WV(2); G8_BAR; G8_WL(0); G8_MMA(0, 0, At, B0); G8_BAR;
;     G8_LDB(B1, 1, 1); G8_WV(0); G8_BAR; G8_WL(0); G8_MMA(0, 1, At, B1); G8_BAR;
;     G8_LDA(At, 1, 1); G8_BAR; G8_WL(0); G8_MMA(1, 0, At, B0); G8_MMA(1, 1, At, B1); G8_BAR; }
;   if (wr == 0) G8_BAR;
	s_waitcnt lgkmcnt(0)
	s_setprio 1
	s_waitcnt lgkmcnt(0)
	v_mfma_f32_16x16x32_bf16 v[126:129], v[130:133], v[158:161], v[126:129]
	v_mfma_f32_16x16x32_bf16 v[122:125], v[138:141], v[158:161], v[122:125]
	v_mfma_f32_16x16x32_bf16 v[118:121], v[130:133], v[166:169], v[118:121]
	v_mfma_f32_16x16x32_bf16 v[114:117], v[138:141], v[166:169], v[114:117]
	v_mfma_f32_16x16x32_bf16 v[110:113], v[130:133], v[174:177], v[110:113]
	v_mfma_f32_16x16x32_bf16 v[106:109], v[138:141], v[174:177], v[106:109]
	v_mfma_f32_16x16x32_bf16 v[102:105], v[130:133], v[186:189], v[102:105]
	v_mfma_f32_16x16x32_bf16 v[98:101], v[138:141], v[186:189], v[98:101]
	v_mfma_f32_16x16x32_bf16 v[126:129], v[134:137], v[162:165], v[126:129]
	v_mfma_f32_16x16x32_bf16 v[122:125], v[154:157], v[162:165], v[122:125]
	v_mfma_f32_16x16x32_bf16 v[118:121], v[134:137], v[170:173], v[118:121]
	v_mfma_f32_16x16x32_bf16 v[114:117], v[154:157], v[170:173], v[114:117]
	v_mfma_f32_16x16x32_bf16 v[110:113], v[134:137], v[178:181], v[110:113]
	v_mfma_f32_16x16x32_bf16 v[106:109], v[154:157], v[178:181], v[106:109]
	v_mfma_f32_16x16x32_bf16 v[102:105], v[134:137], v[190:193], v[102:105]
	v_mfma_f32_16x16x32_bf16 v[98:101], v[154:157], v[190:193], v[98:101]
	s_setprio 0
	s_barrier
	ds_read_b128 v[194:197], v152
	ds_read_b128 v[198:201], v152 offset:1024
	ds_read_b128 v[202:205], v152 offset:2048
	ds_read_b128 v[150:153], v152 offset:3072
	s_waitcnt vmcnt(0)
	s_barrier
	s_waitcnt lgkmcnt(0)
	s_setprio 1
	s_waitcnt lgkmcnt(0)
	v_mfma_f32_16x16x32_bf16 v[94:97], v[194:197], v[158:161], v[94:97]
	v_mfma_f32_16x16x32_bf16 v[90:93], v[202:205], v[158:161], v[90:93]
	v_mfma_f32_16x16x32_bf16 v[86:89], v[194:197], v[166:169], v[86:89]
	v_mfma_f32_16x16x32_bf16 v[82:85], v[202:205], v[166:169], v[82:85]
	v_mfma_f32_16x16x32_bf16 v[78:81], v[194:197], v[174:177], v[78:81]
	v_mfma_f32_16x16x32_bf16 v[74:77], v[202:205], v[174:177], v[74:77]
	v_mfma_f32_16x16x32_bf16 v[70:73], v[194:197], v[186:189], v[70:73]
	v_mfma_f32_16x16x32_bf16 v[66:69], v[202:205], v[186:189], v[66:69]
	v_mfma_f32_16x16x32_bf16 v[94:97], v[198:201], v[162:165], v[94:97]
	v_mfma_f32_16x16x32_bf16 v[90:93], v[150:153], v[162:165], v[90:93]
	v_mfma_f32_16x16x32_bf16 v[86:89], v[198:201], v[170:173], v[86:89]
	v_mfma_f32_16x16x32_bf16 v[82:85], v[150:153], v[170:173], v[82:85]
	v_mfma_f32_16x16x32_bf16 v[78:81], v[198:201], v[178:181], v[78:81]
	v_mfma_f32_16x16x32_bf16 v[74:77], v[150:153], v[178:181], v[74:77]
	v_mfma_f32_16x16x32_bf16 v[70:73], v[198:201], v[190:193], v[70:73]
	v_mfma_f32_16x16x32_bf16 v[66:69], v[150:153], v[190:193], v[66:69]
	s_setprio 0
	s_barrier
	ds_read_b128 v[158:161], v148 offset:49152
	ds_read_b128 v[162:165], v148 offset:50176
	ds_read_b128 v[166:169], v147 offset:49152
	ds_read_b128 v[170:173], v147 offset:50176
	ds_read_b128 v[174:177], v146 offset:49152
	ds_read_b128 v[146:149], v146 offset:50176
	ds_read_b128 v[178:181], v144 offset:49152
	ds_read_b128 v[186:189], v144 offset:50176
	s_barrier
	s_waitcnt lgkmcnt(0)
	s_setprio 1
	s_waitcnt lgkmcnt(0)
	v_mfma_f32_16x16x32_bf16 v[62:65], v[130:133], v[158:161], v[62:65]
	v_mfma_f32_16x16x32_bf16 v[58:61], v[138:141], v[158:161], v[58:61]
	v_mfma_f32_16x16x32_bf16 v[54:57], v[130:133], v[166:169], v[54:57]
	v_mfma_f32_16x16x32_bf16 v[50:53], v[138:141], v[166:169], v[50:53]
	v_mfma_f32_16x16x32_bf16 v[46:49], v[130:133], v[174:177], v[46:49]
	v_mfma_f32_16x16x32_bf16 v[42:45], v[138:141], v[174:177], v[42:45]
	v_mfma_f32_16x16x32_bf16 v[38:41], v[130:133], v[178:181], v[38:41]
	v_mfma_f32_16x16x32_bf16 v[34:37], v[138:141], v[178:181], v[34:37]
	v_mfma_f32_16x16x32_bf16 v[62:65], v[134:137], v[162:165], v[62:65]
	v_mfma_f32_16x16x32_bf16 v[58:61], v[154:157], v[162:165], v[58:61]
	v_mfma_f32_16x16x32_bf16 v[54:57], v[134:137], v[170:173], v[54:57]
	v_mfma_f32_16x16x32_bf16 v[50:53], v[154:157], v[170:173], v[50:53]
	v_mfma_f32_16x16x32_bf16 v[46:49], v[134:137], v[146:149], v[46:49]
	v_mfma_f32_16x16x32_bf16 v[42:45], v[154:157], v[146:149], v[42:45]
	v_mfma_f32_16x16x32_bf16 v[38:41], v[134:137], v[186:189], v[38:41]
	v_mfma_f32_16x16x32_bf16 v[34:37], v[154:157], v[186:189], v[34:37]
	s_setprio 0
	s_setprio 1
	v_mfma_f32_16x16x32_bf16 v[30:33], v[194:197], v[158:161], v[30:33]
	v_mfma_f32_16x16x32_bf16 v[26:29], v[202:205], v[158:161], v[26:29]
	v_mfma_f32_16x16x32_bf16 v[22:25], v[194:197], v[166:169], v[22:25]
	v_mfma_f32_16x16x32_bf16 v[18:21], v[202:205], v[166:169], v[18:21]
	v_mfma_f32_16x16x32_bf16 v[14:17], v[194:197], v[174:177], v[14:17]
	v_mfma_f32_16x16x32_bf16 v[10:13], v[202:205], v[174:177], v[10:13]
	v_mfma_f32_16x16x32_bf16 v[6:9], v[194:197], v[178:181], v[6:9]
	v_mfma_f32_16x16x32_bf16 v[0:3], v[202:205], v[178:181], v[0:3]
	v_mfma_f32_16x16x32_bf16 v[30:33], v[198:201], v[162:165], v[30:33]
	v_mfma_f32_16x16x32_bf16 v[26:29], v[150:153], v[162:165], v[26:29]
	v_mfma_f32_16x16x32_bf16 v[22:25], v[198:201], v[170:173], v[22:25]
	v_mfma_f32_16x16x32_bf16 v[18:21], v[150:153], v[170:173], v[18:21]
	v_mfma_f32_16x16x32_bf16 v[14:17], v[198:201], v[146:149], v[14:17]
	v_mfma_f32_16x16x32_bf16 v[10:13], v[150:153], v[146:149], v[10:13]
	v_mfma_f32_16x16x32_bf16 v[6:9], v[198:201], v[186:189], v[6:9]
	v_mfma_f32_16x16x32_bf16 v[0:3], v[150:153], v[186:189], v[0:3]
	s_setprio 0
	s_movk_i32 s5, 0x100
	v_cmp_gt_u32_e32 vcc, s5, v143
	s_barrier
	s_and_saveexec_b64 s[8:9], vcc
	s_cbranch_execz .LBB0_521
	s_barrier
	s_branch .LBB0_521
